# v110: v106 with the s_sleep removed from the three polling loops (panel hand-off in the folded epilogue, transposing-norm hand-off, grid barrier top counter)
# speedup vs baseline: 1.0130x; 1.0130x over previous
.Lrf_poll:
	global_load_dword v251, v1, s[8:9] sc1
	s_waitcnt vmcnt(0)
	v_readfirstlane_b32 s12, v251
	s_cmp_ge_u32 s12, 4
	s_cbranch_scc1 .Lrf_ok
	s_add_i32 s2, s2, 1
	s_cmp_gt_u32 s2, 0x20000
	s_cbranch_scc1 .Lrf_ok
	s_nop 0
	s_branch .Lrf_poll

.Lnt_poll:
	global_load_dword v200, v1, s[10:11] sc1
	s_waitcnt vmcnt(0)
	v_readfirstlane_b32 s1, v200
	s_cmp_ge_u32 s1, 4
	s_cbranch_scc1 .Lnt_ok
	s_add_i32 s0, s0, 1
	s_cmp_gt_u32 s0, 0x20000
	s_cbranch_scc1 .Lnt_ok
	s_nop 0
	s_branch .Lnt_poll

.Lxb_spin:
	global_load_dword v6, v1, s[10:11] sc1
	s_waitcnt vmcnt(0)
	v_cmp_ge_u32_e32 vcc, v6, v5
	s_cbranch_vccnz .Lxb_done
	s_add_i32 s8, s8, 1
	s_cmp_gt_u32 s8, 0x100000
	s_cbranch_scc1 .Lxb_done
	s_nop 0
	s_branch .Lxb_spin
